# GEMM4: first K-iteration after an epilogue runs from a copy whose first two waits are vmcnt(16), so they do not drain the epilogue stores
# baseline (speedup 1.0000x reference)
;     __device__ __forceinline__ const char* aptr(const Unit& u, const Gemm& g) const { return (const char*)g.A + (long)(u.pm >> 4) * g.adj; }
;     __device__ __forceinline__ const char* bptr(const Unit&, const Gemm& g) const { return (const char*)g.Bt; }
; #define PG8_STAGE(bufoff, gbase, voff) do { _Pragma("unroll") for (int _i = 0; _i < 2; ++_i) \
;         __builtin_amdgcn_global_load_lds((const unsigned*)((const char*)(gbase) + (voff)[_i]), (PG8_LAS unsigned*)(lds + (bufoff) + ldsw + _i * 8192), 16, 0, 0); } while (0)
; #define PG8_LDA(dst, b, h) do { _Pragma("unroll") for (int m = 0; m < 4; ++m) _Pragma("unroll") for (int k = 0; k < 2; ++k) dst[m][k] = *(const PG8_LAS bf16x8*)(lds + PG8_SA(b, h) + aoff + m * 2048 + k * 1024); } while (0)
; #define PG8_WAIT_V(n) asm volatile("s_waitcnt vmcnt(" #n ")" ::: "memory")
; #define PG8_WAIT_L(n) asm volatile("s_waitcnt lgkmcnt(" #n ")" ::: "memory")
; template <class Epi, class Sched, bool ALIGN_EPI = false, bool SP2 = false>
; __device__ __forceinline__ void gemm_phase(PG8_LAS unsigned char* lds, const Gemm g, const Sched& S, const Epi& E) {
;     ...
;     for (;;) {
;         const bool has_next = S.next(ui + 1, nxt);
;         const char* nA = has_next ? S.aptr(nxt, g) + (size_t)nxt.pm * tstep : cA; const char* nB = has_next ? S.bptr(nxt, g) + (size_t)nxt.pn * tstep : cB;
;         for (int t = 0; t < nt; t += 2) {
;             const bool last = (t == nt - 2);
;             const char* a1 = cA + (size_t)(t + 1) * kstep;
;             const char* a2 = last ? nA : cA + (size_t)(t + 2) * kstep; const char* b2 = last ? nB : cB + (size_t)(t + 2) * kstep;
;             const char* a3 = a2 + kstep; const char* b3 = b2 + kstep;
;             if (last && has_next) S.a_ready(nxt);
;             if constexpr (SP2) {
;             PG8_LDB(B0, 0, 0); PG8_LDB(B1, 0, 1); PG8_SCHED; PG8_LDA(At, 0, 0); PG8_STAGE(PG8_SA(1, 1), a1 + hstep, voffA);
;             PG8_WAIT_V(8); PG8_WAIT_L(0); PG8_BAR; PG8_MMA(0, 0, At, B0); PG8_MMA(0, 1, At, B1); PG8_BAR; PG8_SCHED;
;     ...
;         if (epi_now) {
; #pragma unroll
;         for (int a = 0; a < 2; ++a)
; #pragma unroll
;             for (int b = 0; b < 2; ++b)
; #pragma unroll
;                 for (int m = 0; m < 4; ++m)
; #pragma unroll
;                     for (int n = 0; n < 2; ++n) acc[a][b][m][n] = (f32x4){0.f, 0.f, 0.f, 0.f};
;         }
;         cur = nxt; cA = nA; cB = nB; ++ui;
.LBB0_573:
	s_andn2_b64 vcc, exec, s[42:43]
	s_mov_b32 s59, s26
	s_mov_b32 s42, s28
	s_mov_b64 s[46:47], s[34:35]
	s_mov_b64 s[44:45], s[30:31]
	s_cbranch_vccz .LBB0_583
	s_add_i32 s58, s58, 1
	s_mul_i32 s10, s58, s33
	s_mul_hi_u32 s11, s58, s86
	s_add_i32 s11, s11, s10
	s_mul_i32 s10, s58, s86
	s_add_u32 s30, s10, s97
	s_addc_u32 s31, s11, s50
	v_mov_b64_e32 v[0:1], 0xb00
	v_cmp_lt_i64_e64 s[40:41], s[30:31], v[0:1]
	v_mov_b64_e32 v[0:1], 0xaff
	v_cmp_gt_i64_e32 vcc, s[30:31], v[0:1]
	s_cbranch_vccnz .Lh4_576
	s_ashr_i32 s10, s30, 31
	s_lshr_b32 s10, s10, 29
	s_add_i32 s10, s30, s10
	s_ashr_i32 s11, s10, 3
	s_and_b32 s10, s10, -8
	s_sub_i32 s10, s30, s10
	s_cmp_lt_i32 s10, 0
	s_cselect_b32 s26, s5, 0x160
	s_mul_i32 s10, s10, s26
	s_add_i32 s10, s10, s11
	s_mul_hi_i32 s11, s10, 0x2e8ba2e9
	s_lshr_b32 s26, s11, 31
	s_ashr_i32 s11, s11, 5
	s_add_i32 s11, s11, s26
	s_lshl_b32 s27, s11, 3
	s_sub_i32 s26, 0x80, s27
	s_min_i32 s28, s26, 8
	s_abs_i32 s26, s28
	v_cvt_f32_u32_e32 v0, s26
	s_sub_i32 s30, 0, s26
	s_mulk_i32 s11, 0xb0
	s_sub_i32 s10, s10, s11
	v_rcp_iflag_f32_e32 v0, v0
	s_abs_i32 s11, s10
	s_xor_b32 s29, s10, s28
	s_ashr_i32 s29, s29, 31
	v_mul_f32_e32 v0, 0x4f7ffffe, v0
	v_cvt_u32_f32_e32 v0, v0
	s_nop 0
	v_readfirstlane_b32 s31, v0
	s_mul_i32 s30, s30, s31
	s_mul_hi_u32 s30, s31, s30
	s_add_i32 s31, s31, s30
	s_mul_hi_u32 s30, s11, s31
	s_mul_i32 s31, s30, s26
	s_sub_i32 s11, s11, s31
	s_add_i32 s34, s30, 1
	s_sub_i32 s31, s11, s26
	s_cmp_ge_u32 s11, s26
	s_cselect_b32 s30, s34, s30
	s_cselect_b32 s11, s31, s11
	s_add_i32 s31, s30, 1
	s_cmp_ge_u32 s11, s26
	s_cselect_b32 s11, s31, s30
	s_xor_b32 s11, s11, s29
	s_sub_i32 s26, s11, s29
	s_mul_i32 s11, s26, s28
	s_sub_i32 s10, s10, s11
	s_add_i32 s28, s27, s10
.Lh4_576:
	s_ashr_i32 s29, s28, 31
	s_lshl_b64 s[10:11], s[28:29], 19
	s_add_u32 s30, s3, s10
	s_addc_u32 s31, s8, s11
	s_and_b64 s[10:11], s[40:41], exec
	s_cselect_b32 s29, s31, s45
	s_cselect_b32 s43, s30, s44
	s_ashr_i32 s27, s26, 31
	s_lshl_b64 s[10:11], s[26:27], 19
	s_add_u32 s34, s14, s10
	s_addc_u32 s35, s18, s11
	s_and_b64 s[10:11], s[40:41], exec
	s_cselect_b32 s27, s35, s47
	s_cselect_b32 s60, s34, s46
	s_add_u32 s44, s44, 0x40080
	s_addc_u32 s45, s45, 0
	s_add_u32 s61, s46, 0x100
	v_mov_b32_e32 v0, 0
	s_addc_u32 s62, s47, 0
	s_mov_b32 s63, -2
	v_mov_b64_e32 v[0:1], 0
	v_mov_b64_e32 v[2:3], 0
	v_mov_b64_e32 v[8:9], 0
	v_mov_b64_e32 v[10:11], 0
	v_mov_b64_e32 v[16:17], 0
	v_mov_b64_e32 v[18:19], 0
	v_mov_b64_e32 v[24:25], 0
	v_mov_b64_e32 v[26:27], 0
	v_mov_b64_e32 v[32:33], 0
	v_mov_b64_e32 v[34:35], 0
	v_mov_b64_e32 v[40:41], 0
	v_mov_b64_e32 v[42:43], 0
	v_mov_b64_e32 v[48:49], 0
	v_mov_b64_e32 v[50:51], 0
	v_mov_b64_e32 v[56:57], 0
	v_mov_b64_e32 v[58:59], 0
	v_mov_b64_e32 v[4:5], 0
	v_mov_b64_e32 v[6:7], 0
	v_mov_b64_e32 v[12:13], 0
	v_mov_b64_e32 v[14:15], 0
	v_mov_b64_e32 v[20:21], 0
	v_mov_b64_e32 v[22:23], 0
	v_mov_b64_e32 v[28:29], 0
	v_mov_b64_e32 v[30:31], 0
	v_mov_b64_e32 v[36:37], 0
	v_mov_b64_e32 v[38:39], 0
	v_mov_b64_e32 v[44:45], 0
	v_mov_b64_e32 v[46:47], 0
	v_mov_b64_e32 v[52:53], 0
	v_mov_b64_e32 v[54:55], 0
	v_mov_b64_e32 v[60:61], 0
	v_mov_b64_e32 v[62:63], 0
	v_mov_b64_e32 v[64:65], 0
	v_mov_b64_e32 v[66:67], 0
	v_mov_b64_e32 v[72:73], 0
	v_mov_b64_e32 v[74:75], 0
	v_mov_b64_e32 v[80:81], 0
	v_mov_b64_e32 v[82:83], 0
	v_mov_b64_e32 v[88:89], 0
	v_mov_b64_e32 v[90:91], 0
	v_mov_b64_e32 v[96:97], 0
	v_mov_b64_e32 v[98:99], 0
	v_mov_b64_e32 v[104:105], 0
	v_mov_b64_e32 v[106:107], 0
	v_mov_b64_e32 v[112:113], 0
	v_mov_b64_e32 v[114:115], 0
	v_mov_b64_e32 v[120:121], 0
	v_mov_b64_e32 v[122:123], 0
	v_mov_b64_e32 v[68:69], 0
	v_mov_b64_e32 v[70:71], 0
	v_mov_b64_e32 v[76:77], 0
	v_mov_b64_e32 v[78:79], 0
	v_mov_b64_e32 v[84:85], 0
	v_mov_b64_e32 v[86:87], 0
	v_mov_b64_e32 v[92:93], 0
	v_mov_b64_e32 v[94:95], 0
	v_mov_b64_e32 v[100:101], 0
	v_mov_b64_e32 v[102:103], 0
	v_mov_b64_e32 v[108:109], 0
	v_mov_b64_e32 v[110:111], 0
	v_mov_b64_e32 v[116:117], 0
	v_mov_b64_e32 v[118:119], 0
	v_mov_b64_e32 v[124:125], 0
	v_mov_b64_e32 v[126:127], 0
	s_add_u32 s10, s44, 0xfffc0080
	s_addc_u32 s11, s45, -1
	s_add_i32 s64, 0, 0x10000
	s_cmp_eq_u32 s63, 12
	s_cselect_b32 s49, s29, s11
	s_cselect_b32 s48, s43, s10
	v_add_u32_e32 v146, s64, v149
	s_cselect_b32 s47, s27, s62
	s_cselect_b32 s46, s60, s61
	s_add_i32 s65, 0, 0x14000
	ds_read_b128 v[128:131], v146
	ds_read_b128 v[154:157], v146 offset:1024
	ds_read_b128 v[158:161], v146 offset:2048
	ds_read_b128 v[162:165], v146 offset:3072
	v_add_u32_e32 v146, s65, v149
	ds_read_b128 v[166:169], v146
	ds_read_b128 v[170:173], v146 offset:1024
	ds_read_b128 v[174:177], v146 offset:2048
	ds_read_b128 v[178:181], v146 offset:3072
	v_lshl_add_u64 v[190:191], s[44:45], 0, v[142:143]
	s_add_i32 m0, s51, 0xc000
	ds_read_b128 v[182:185], v153
	ds_read_b128 v[186:189], v153 offset:1024
	ds_read_b128 v[194:197], v153 offset:2048
	ds_read_b128 v[198:201], v153 offset:3072
	ds_read_b128 v[202:205], v153 offset:4096
	ds_read_b128 v[206:209], v153 offset:5120
	ds_read_b128 v[210:213], v153 offset:6144
	ds_read_b128 v[214:217], v153 offset:7168
	global_load_lds_dwordx4 v[190:191], off
	v_lshl_add_u64 v[190:191], s[44:45], 0, v[144:145]
	s_add_i32 m0, s51, 0xe000
	s_nop 0
	global_load_lds_dwordx4 v[190:191], off
	s_waitcnt vmcnt(16)
	s_waitcnt lgkmcnt(0)
	s_barrier
; #define PG8_STAGE(bufoff, gbase, voff) do { _Pragma("unroll") for (int _i = 0; _i < 2; ++_i) \
;         __builtin_amdgcn_global_load_lds((const unsigned*)((const char*)(gbase) + (voff)[_i]), (PG8_LAS unsigned*)(lds + (bufoff) + ldsw + _i * 8192), 16, 0, 0); } while (0)
; #define PG8_LDA(dst, b, h) do { _Pragma("unroll") for (int m = 0; m < 4; ++m) _Pragma("unroll") for (int k = 0; k < 2; ++k) dst[m][k] = *(const PG8_LAS bf16x8*)(lds + PG8_SA(b, h) + aoff + m * 2048 + k * 1024); } while (0)
; #define PG8_MMA(ai, bj, At, Bt) do { __builtin_amdgcn_s_setprio(1); _Pragma("unroll") for (int m = 0; m < 4; ++m) _Pragma("unroll") for (int n = 0; n < 2; ++n) _Pragma("unroll") for (int k = 0; k < 2; ++k) \
;         acc[ai][bj][m][n] = __builtin_amdgcn_mfma_f32_16x16x32_bf16(Bt[n][k], At[m][k], acc[ai][bj][m][n], 0, 0, 0); __builtin_amdgcn_s_setprio(0); } while (0)
; #define PG8_WAIT_V(n) asm volatile("s_waitcnt vmcnt(" #n ")" ::: "memory")
; #define PG8_WAIT_L(n) asm volatile("s_waitcnt lgkmcnt(" #n ")" ::: "memory")
; #define PG8_BAR __builtin_amdgcn_s_barrier()
; #define PG8_SCHED __builtin_amdgcn_sched_barrier(0)
; template <class Epi, class Sched, bool ALIGN_EPI = false, bool SP2 = false>
; __device__ __forceinline__ void gemm_phase(PG8_LAS unsigned char* lds, const Gemm g, const Sched& S, const Epi& E) {
;     ...
;             PG8_WAIT_V(8); PG8_WAIT_L(0); PG8_BAR; PG8_MMA(0, 0, At, B0); PG8_MMA(0, 1, At, B1); PG8_BAR; PG8_SCHED;
;             PG8_LDA(At, 0, 1); PG8_STAGE(PG8_SB(0, 0), b2, voffB); PG8_STAGE(PG8_SB(0, 1), b2 + hstep, voffB); PG8_STAGE(PG8_SA(0, 0), a2, voffA);
;             PG8_WAIT_V(8); PG8_WAIT_L(0); PG8_BAR; PG8_MMA(1, 0, At, B0); PG8_MMA(1, 1, At, B1); PG8_BAR; PG8_SCHED;
	s_setprio 1
	s_waitcnt lgkmcnt(0)
	v_mfma_f32_16x16x32_bf16 v[124:127], v[128:131], v[182:185], v[124:127]
	v_mfma_f32_16x16x32_bf16 v[116:119], v[158:161], v[182:185], v[116:119]
	v_mfma_f32_16x16x32_bf16 v[108:111], v[128:131], v[194:197], v[108:111]
	v_mfma_f32_16x16x32_bf16 v[100:103], v[158:161], v[194:197], v[100:103]
	v_mfma_f32_16x16x32_bf16 v[92:95], v[128:131], v[202:205], v[92:95]
	v_mfma_f32_16x16x32_bf16 v[84:87], v[158:161], v[202:205], v[84:87]
	v_mfma_f32_16x16x32_bf16 v[76:79], v[128:131], v[210:213], v[76:79]
	v_mfma_f32_16x16x32_bf16 v[68:71], v[158:161], v[210:213], v[68:71]
	v_mfma_f32_16x16x32_bf16 v[124:127], v[154:157], v[186:189], v[124:127]
	v_mfma_f32_16x16x32_bf16 v[116:119], v[162:165], v[186:189], v[116:119]
	v_mfma_f32_16x16x32_bf16 v[108:111], v[154:157], v[198:201], v[108:111]
	v_mfma_f32_16x16x32_bf16 v[100:103], v[162:165], v[198:201], v[100:103]
	v_mfma_f32_16x16x32_bf16 v[92:95], v[154:157], v[206:209], v[92:95]
	v_mfma_f32_16x16x32_bf16 v[84:87], v[162:165], v[206:209], v[84:87]
	v_mfma_f32_16x16x32_bf16 v[76:79], v[154:157], v[214:217], v[76:79]
	v_mfma_f32_16x16x32_bf16 v[68:71], v[162:165], v[214:217], v[68:71]
	s_setprio 0
	s_setprio 1
	v_mfma_f32_16x16x32_bf16 v[120:123], v[166:169], v[182:185], v[120:123]
	v_mfma_f32_16x16x32_bf16 v[112:115], v[174:177], v[182:185], v[112:115]
	v_mfma_f32_16x16x32_bf16 v[104:107], v[166:169], v[194:197], v[104:107]
	v_mfma_f32_16x16x32_bf16 v[96:99], v[174:177], v[194:197], v[96:99]
	v_mfma_f32_16x16x32_bf16 v[88:91], v[166:169], v[202:205], v[88:91]
	v_mfma_f32_16x16x32_bf16 v[80:83], v[174:177], v[202:205], v[80:83]
	v_mfma_f32_16x16x32_bf16 v[72:75], v[166:169], v[210:213], v[72:75]
	v_mfma_f32_16x16x32_bf16 v[64:67], v[174:177], v[210:213], v[64:67]
	v_mfma_f32_16x16x32_bf16 v[120:123], v[170:173], v[186:189], v[120:123]
	v_mfma_f32_16x16x32_bf16 v[112:115], v[178:181], v[186:189], v[112:115]
	v_mfma_f32_16x16x32_bf16 v[104:107], v[170:173], v[198:201], v[104:107]
	v_mfma_f32_16x16x32_bf16 v[96:99], v[178:181], v[198:201], v[96:99]
	v_mfma_f32_16x16x32_bf16 v[88:91], v[170:173], v[206:209], v[88:91]
	v_mfma_f32_16x16x32_bf16 v[80:83], v[178:181], v[206:209], v[80:83]
	v_mfma_f32_16x16x32_bf16 v[72:75], v[170:173], v[214:217], v[72:75]
	v_mfma_f32_16x16x32_bf16 v[64:67], v[178:181], v[214:217], v[64:67]
	s_setprio 0
	s_barrier
	s_add_i32 s10, s64, s19
	v_lshl_add_u64 v[190:191], s[46:47], 0, v[136:137]
	s_mov_b32 m0, s10
	ds_read_b128 v[182:185], v153 offset:16384
	ds_read_b128 v[186:189], v153 offset:17408
	ds_read_b128 v[194:197], v153 offset:18432
	ds_read_b128 v[198:201], v153 offset:19456
	ds_read_b128 v[202:205], v153 offset:20480
	ds_read_b128 v[206:209], v153 offset:21504
	ds_read_b128 v[210:213], v153 offset:22528
	ds_read_b128 v[214:217], v153 offset:23552
	global_load_lds_dwordx4 v[190:191], off
	s_add_i32 m0, s10, 0x2000
	s_add_u32 s10, s46, 0x40000
	v_lshl_add_u64 v[218:219], s[46:47], 0, v[132:133]
	s_addc_u32 s11, s47, 0
	s_add_i32 s64, s65, s19
	global_load_lds_dwordx4 v[218:219], off
	v_lshl_add_u64 v[220:221], s[10:11], 0, v[136:137]
	s_mov_b32 m0, s64
	v_lshl_add_u64 v[222:223], s[48:49], 0, v[134:135]
	global_load_lds_dwordx4 v[220:221], off
	v_lshl_add_u64 v[220:221], s[10:11], 0, v[132:133]
	s_add_i32 m0, s64, 0x2000
	s_nop 0
	global_load_lds_dwordx4 v[220:221], off
	v_lshl_add_u64 v[220:221], s[48:49], 0, v[138:139]
	s_mov_b32 m0, s51
	s_nop 0
	global_load_lds_dwordx4 v[220:221], off
	s_mov_b32 m0, s52
	s_nop 0
	global_load_lds_dwordx4 v[222:223], off
	s_waitcnt vmcnt(16)
	s_waitcnt lgkmcnt(0)
	s_barrier
	s_setprio 1
	s_waitcnt lgkmcnt(0)
	v_mfma_f32_16x16x32_bf16 v[60:63], v[128:131], v[182:185], v[60:63]
	v_mfma_f32_16x16x32_bf16 v[52:55], v[158:161], v[182:185], v[52:55]
	v_mfma_f32_16x16x32_bf16 v[44:47], v[128:131], v[194:197], v[44:47]
	v_mfma_f32_16x16x32_bf16 v[36:39], v[158:161], v[194:197], v[36:39]
	v_mfma_f32_16x16x32_bf16 v[28:31], v[128:131], v[202:205], v[28:31]
	v_mfma_f32_16x16x32_bf16 v[20:23], v[158:161], v[202:205], v[20:23]
	v_mfma_f32_16x16x32_bf16 v[12:15], v[128:131], v[210:213], v[12:15]
	v_mfma_f32_16x16x32_bf16 v[4:7], v[158:161], v[210:213], v[4:7]
	v_mfma_f32_16x16x32_bf16 v[60:63], v[154:157], v[186:189], v[60:63]
	v_mfma_f32_16x16x32_bf16 v[52:55], v[162:165], v[186:189], v[52:55]
	v_mfma_f32_16x16x32_bf16 v[44:47], v[154:157], v[198:201], v[44:47]
	v_mfma_f32_16x16x32_bf16 v[36:39], v[162:165], v[198:201], v[36:39]
	v_mfma_f32_16x16x32_bf16 v[28:31], v[154:157], v[206:209], v[28:31]
	v_mfma_f32_16x16x32_bf16 v[20:23], v[162:165], v[206:209], v[20:23]
	v_mfma_f32_16x16x32_bf16 v[12:15], v[154:157], v[214:217], v[12:15]
	v_mfma_f32_16x16x32_bf16 v[4:7], v[162:165], v[214:217], v[4:7]
	s_setprio 0
	s_setprio 1
	v_mfma_f32_16x16x32_bf16 v[56:59], v[166:169], v[182:185], v[56:59]
	v_mfma_f32_16x16x32_bf16 v[48:51], v[174:177], v[182:185], v[48:51]
	v_mfma_f32_16x16x32_bf16 v[40:43], v[166:169], v[194:197], v[40:43]
	v_mfma_f32_16x16x32_bf16 v[32:35], v[174:177], v[194:197], v[32:35]
	v_mfma_f32_16x16x32_bf16 v[24:27], v[166:169], v[202:205], v[24:27]
	v_mfma_f32_16x16x32_bf16 v[16:19], v[174:177], v[202:205], v[16:19]
	v_mfma_f32_16x16x32_bf16 v[8:11], v[166:169], v[210:213], v[8:11]
	v_mfma_f32_16x16x32_bf16 v[0:3], v[174:177], v[210:213], v[0:3]
	v_mfma_f32_16x16x32_bf16 v[56:59], v[170:173], v[186:189], v[56:59]
	v_mfma_f32_16x16x32_bf16 v[48:51], v[178:181], v[186:189], v[48:51]
	v_mfma_f32_16x16x32_bf16 v[40:43], v[170:173], v[198:201], v[40:43]
	v_mfma_f32_16x16x32_bf16 v[32:35], v[178:181], v[198:201], v[32:35]
	v_mfma_f32_16x16x32_bf16 v[24:27], v[170:173], v[206:209], v[24:27]
	v_mfma_f32_16x16x32_bf16 v[16:19], v[178:181], v[206:209], v[16:19]
	v_mfma_f32_16x16x32_bf16 v[8:11], v[170:173], v[214:217], v[8:11]
	v_mfma_f32_16x16x32_bf16 v[0:3], v[178:181], v[214:217], v[0:3]
	s_setprio 0
	s_barrier
; #define PG8_STAGE(bufoff, gbase, voff) do { _Pragma("unroll") for (int _i = 0; _i < 2; ++_i) \
;         __builtin_amdgcn_global_load_lds((const unsigned*)((const char*)(gbase) + (voff)[_i]), (PG8_LAS unsigned*)(lds + (bufoff) + ldsw + _i * 8192), 16, 0, 0); } while (0)
; #define PG8_LDA(dst, b, h) do { _Pragma("unroll") for (int m = 0; m < 4; ++m) _Pragma("unroll") for (int k = 0; k < 2; ++k) dst[m][k] = *(const PG8_LAS bf16x8*)(lds + PG8_SA(b, h) + aoff + m * 2048 + k * 1024); } while (0)
; #define PG8_LDB(dst, b, h) do { _Pragma("unroll") for (int n = 0; n < 2; ++n) _Pragma("unroll") for (int k = 0; k < 2; ++k) dst[n][k] = *(const PG8_LAS bf16x8*)(lds + PG8_SB(b, h) + boff + n * 2048 + k * 1024); } while (0)
; #define PG8_MMA(ai, bj, At, Bt) do { __builtin_amdgcn_s_setprio(1); _Pragma("unroll") for (int m = 0; m < 4; ++m) _Pragma("unroll") for (int n = 0; n < 2; ++n) _Pragma("unroll") for (int k = 0; k < 2; ++k) \
;         acc[ai][bj][m][n] = __builtin_amdgcn_mfma_f32_16x16x32_bf16(Bt[n][k], At[m][k], acc[ai][bj][m][n], 0, 0, 0); __builtin_amdgcn_s_setprio(0); } while (0)
; #define PG8_WAIT_V(n) asm volatile("s_waitcnt vmcnt(" #n ")" ::: "memory")
; #define PG8_WAIT_L(n) asm volatile("s_waitcnt lgkmcnt(" #n ")" ::: "memory")
; #define PG8_BAR __builtin_amdgcn_s_barrier()
; #define PG8_SCHED __builtin_amdgcn_sched_barrier(0)
; template <class Epi, class Sched, bool ALIGN_EPI = false, bool SP2 = false>
; __device__ __forceinline__ void gemm_phase(PG8_LAS unsigned char* lds, const Gemm g, const Sched& S, const Epi& E) {
;     ...
;             PG8_LDB(B0, 1, 0); PG8_LDB(B1, 1, 1); PG8_SCHED; PG8_LDA(At, 1, 0); PG8_STAGE(PG8_SA(0, 1), a2 + hstep, voffA);
;             PG8_WAIT_V(8); PG8_WAIT_L(0); PG8_BAR; PG8_MMA(0, 0, At, B0); PG8_MMA(0, 1, At, B1); PG8_BAR; PG8_SCHED;
	s_add_i32 s64, 0, 0x18000
	v_add_u32_e32 v146, s64, v149
	s_add_i32 s65, 0, 0x1c000
	ds_read_b128 v[128:131], v146
	ds_read_b128 v[154:157], v146 offset:1024
	ds_read_b128 v[158:161], v146 offset:2048
	ds_read_b128 v[162:165], v146 offset:3072
	v_add_u32_e32 v146, s65, v149
	ds_read_b128 v[166:169], v146
	ds_read_b128 v[170:173], v146 offset:1024
	ds_read_b128 v[174:177], v146 offset:2048
	ds_read_b128 v[178:181], v146 offset:3072
	s_add_u32 s10, s48, 0x40000
	s_addc_u32 s11, s49, 0
	s_mov_b32 m0, s53
	v_lshl_add_u64 v[224:225], s[10:11], 0, v[138:139]
	ds_read_b128 v[182:185], v153 offset:32768
	ds_read_b128 v[186:189], v153 offset:33792
	ds_read_b128 v[194:197], v153 offset:34816
	ds_read_b128 v[198:201], v153 offset:35840
	ds_read_b128 v[202:205], v153 offset:36864
	ds_read_b128 v[206:209], v153 offset:37888
	ds_read_b128 v[210:213], v153 offset:38912
	ds_read_b128 v[214:217], v153 offset:39936
	global_load_lds_dwordx4 v[224:225], off
	v_lshl_add_u64 v[224:225], s[10:11], 0, v[134:135]
	s_mov_b32 m0, s54
	s_nop 0
	global_load_lds_dwordx4 v[224:225], off
	s_waitcnt vmcnt(8)
	s_waitcnt lgkmcnt(0)
	s_barrier
	s_setprio 1
	s_waitcnt lgkmcnt(0)
	v_mfma_f32_16x16x32_bf16 v[124:127], v[128:131], v[182:185], v[124:127]
	v_mfma_f32_16x16x32_bf16 v[116:119], v[158:161], v[182:185], v[116:119]
	v_mfma_f32_16x16x32_bf16 v[108:111], v[128:131], v[194:197], v[108:111]
	v_mfma_f32_16x16x32_bf16 v[100:103], v[158:161], v[194:197], v[100:103]
	v_mfma_f32_16x16x32_bf16 v[92:95], v[128:131], v[202:205], v[92:95]
	v_mfma_f32_16x16x32_bf16 v[84:87], v[158:161], v[202:205], v[84:87]
	v_mfma_f32_16x16x32_bf16 v[76:79], v[128:131], v[210:213], v[76:79]
	v_mfma_f32_16x16x32_bf16 v[68:71], v[158:161], v[210:213], v[68:71]
	v_mfma_f32_16x16x32_bf16 v[124:127], v[154:157], v[186:189], v[124:127]
	v_mfma_f32_16x16x32_bf16 v[116:119], v[162:165], v[186:189], v[116:119]
	v_mfma_f32_16x16x32_bf16 v[108:111], v[154:157], v[198:201], v[108:111]
	v_mfma_f32_16x16x32_bf16 v[100:103], v[162:165], v[198:201], v[100:103]
	v_mfma_f32_16x16x32_bf16 v[92:95], v[154:157], v[206:209], v[92:95]
	v_mfma_f32_16x16x32_bf16 v[84:87], v[162:165], v[206:209], v[84:87]
	v_mfma_f32_16x16x32_bf16 v[76:79], v[154:157], v[214:217], v[76:79]
	v_mfma_f32_16x16x32_bf16 v[68:71], v[162:165], v[214:217], v[68:71]
	s_setprio 0
	s_setprio 1
	v_mfma_f32_16x16x32_bf16 v[120:123], v[166:169], v[182:185], v[120:123]
	v_mfma_f32_16x16x32_bf16 v[112:115], v[174:177], v[182:185], v[112:115]
	v_mfma_f32_16x16x32_bf16 v[104:107], v[166:169], v[194:197], v[104:107]
	v_mfma_f32_16x16x32_bf16 v[96:99], v[174:177], v[194:197], v[96:99]
	v_mfma_f32_16x16x32_bf16 v[88:91], v[166:169], v[202:205], v[88:91]
	v_mfma_f32_16x16x32_bf16 v[80:83], v[174:177], v[202:205], v[80:83]
	v_mfma_f32_16x16x32_bf16 v[72:75], v[166:169], v[210:213], v[72:75]
	v_mfma_f32_16x16x32_bf16 v[64:67], v[174:177], v[210:213], v[64:67]
	v_mfma_f32_16x16x32_bf16 v[120:123], v[170:173], v[186:189], v[120:123]
	v_mfma_f32_16x16x32_bf16 v[112:115], v[178:181], v[186:189], v[112:115]
	v_mfma_f32_16x16x32_bf16 v[104:107], v[170:173], v[198:201], v[104:107]
	v_mfma_f32_16x16x32_bf16 v[96:99], v[178:181], v[198:201], v[96:99]
	v_mfma_f32_16x16x32_bf16 v[88:91], v[170:173], v[206:209], v[88:91]
	v_mfma_f32_16x16x32_bf16 v[80:83], v[178:181], v[206:209], v[80:83]
	v_mfma_f32_16x16x32_bf16 v[72:75], v[170:173], v[214:217], v[72:75]
	v_mfma_f32_16x16x32_bf16 v[64:67], v[178:181], v[214:217], v[64:67]
	s_setprio 0
	s_barrier
; #define PG8_STAGE(bufoff, gbase, voff) do { _Pragma("unroll") for (int _i = 0; _i < 2; ++_i) \
;         __builtin_amdgcn_global_load_lds((const unsigned*)((const char*)(gbase) + (voff)[_i]), (PG8_LAS unsigned*)(lds + (bufoff) + ldsw + _i * 8192), 16, 0, 0); } while (0)
; #define PG8_LDA(dst, b, h) do { _Pragma("unroll") for (int m = 0; m < 4; ++m) _Pragma("unroll") for (int k = 0; k < 2; ++k) dst[m][k] = *(const PG8_LAS bf16x8*)(lds + PG8_SA(b, h) + aoff + m * 2048 + k * 1024); } while (0)
; #define PG8_MMA(ai, bj, At, Bt) do { __builtin_amdgcn_s_setprio(1); _Pragma("unroll") for (int m = 0; m < 4; ++m) _Pragma("unroll") for (int n = 0; n < 2; ++n) _Pragma("unroll") for (int k = 0; k < 2; ++k) \
;         acc[ai][bj][m][n] = __builtin_amdgcn_mfma_f32_16x16x32_bf16(Bt[n][k], At[m][k], acc[ai][bj][m][n], 0, 0, 0); __builtin_amdgcn_s_setprio(0); } while (0)
; #define PG8_WAIT_V(n) asm volatile("s_waitcnt vmcnt(" #n ")" ::: "memory")
; #define PG8_WAIT_L(n) asm volatile("s_waitcnt lgkmcnt(" #n ")" ::: "memory")
; #define PG8_BAR __builtin_amdgcn_s_barrier()
; #define PG8_SCHED __builtin_amdgcn_sched_barrier(0)
; template <class Epi, class Sched, bool ALIGN_EPI = false, bool SP2 = false>
; __device__ __forceinline__ void gemm_phase(PG8_LAS unsigned char* lds, const Gemm g, const Sched& S, const Epi& E) {
;     ...
;         for (int t = 0; t < nt; t += 2) {
;             const bool last = (t == nt - 2);
;             const char* a1 = cA + (size_t)(t + 1) * kstep;
;             const char* a2 = last ? nA : cA + (size_t)(t + 2) * kstep; const char* b2 = last ? nB : cB + (size_t)(t + 2) * kstep;
;     ...
;             PG8_LDA(At, 1, 1); PG8_STAGE(PG8_SB(1, 0), b3, voffB); PG8_STAGE(PG8_SB(1, 1), b3 + hstep, voffB); PG8_STAGE(PG8_SA(1, 0), a3, voffA);
;             PG8_WAIT_V(8); PG8_WAIT_L(0); PG8_BAR; PG8_MMA(1, 0, At, B0); PG8_MMA(1, 1, At, B1); PG8_BAR; PG8_SCHED;
	s_add_i32 s10, s64, s19
	v_lshl_add_u64 v[190:191], v[190:191], 0, s[36:37]
	s_mov_b32 m0, s10
	ds_read_b128 v[182:185], v153 offset:49152
	ds_read_b128 v[186:189], v153 offset:50176
	ds_read_b128 v[194:197], v153 offset:51200
	ds_read_b128 v[198:201], v153 offset:52224
	ds_read_b128 v[202:205], v153 offset:53248
	ds_read_b128 v[206:209], v153 offset:54272
	ds_read_b128 v[210:213], v153 offset:55296
	ds_read_b128 v[214:217], v153 offset:56320
	global_load_lds_dwordx4 v[190:191], off
	s_add_i32 m0, s10, 0x2000
	s_add_u32 s10, s46, 0x40080
	v_lshl_add_u64 v[190:191], v[218:219], 0, s[36:37]
	s_addc_u32 s11, s47, 0
	s_add_i32 s46, s65, s19
	global_load_lds_dwordx4 v[190:191], off
	v_lshl_add_u64 v[190:191], s[10:11], 0, v[136:137]
	s_mov_b32 m0, s46
	s_nop 0
	global_load_lds_dwordx4 v[190:191], off
	v_lshl_add_u64 v[190:191], s[10:11], 0, v[132:133]
	s_add_i32 m0, s46, 0x2000
	s_nop 0
	global_load_lds_dwordx4 v[190:191], off
	v_lshl_add_u64 v[190:191], v[220:221], 0, s[36:37]
	s_mov_b32 m0, s20
	s_nop 0
	global_load_lds_dwordx4 v[190:191], off
	v_lshl_add_u64 v[190:191], v[222:223], 0, s[36:37]
	s_mov_b32 m0, s55
	s_nop 0
	global_load_lds_dwordx4 v[190:191], off
	s_waitcnt vmcnt(8)
	s_waitcnt lgkmcnt(0)
	s_barrier
	s_setprio 1
	s_waitcnt lgkmcnt(0)
	v_mfma_f32_16x16x32_bf16 v[60:63], v[128:131], v[182:185], v[60:63]
	v_mfma_f32_16x16x32_bf16 v[52:55], v[158:161], v[182:185], v[52:55]
	v_mfma_f32_16x16x32_bf16 v[44:47], v[128:131], v[194:197], v[44:47]
	v_mfma_f32_16x16x32_bf16 v[36:39], v[158:161], v[194:197], v[36:39]
	v_mfma_f32_16x16x32_bf16 v[28:31], v[128:131], v[202:205], v[28:31]
	v_mfma_f32_16x16x32_bf16 v[20:23], v[158:161], v[202:205], v[20:23]
	v_mfma_f32_16x16x32_bf16 v[12:15], v[128:131], v[210:213], v[12:15]
	v_mfma_f32_16x16x32_bf16 v[4:7], v[158:161], v[210:213], v[4:7]
	v_mfma_f32_16x16x32_bf16 v[60:63], v[154:157], v[186:189], v[60:63]
	v_mfma_f32_16x16x32_bf16 v[52:55], v[162:165], v[186:189], v[52:55]
	v_mfma_f32_16x16x32_bf16 v[44:47], v[154:157], v[198:201], v[44:47]
	v_mfma_f32_16x16x32_bf16 v[36:39], v[162:165], v[198:201], v[36:39]
	v_mfma_f32_16x16x32_bf16 v[28:31], v[154:157], v[206:209], v[28:31]
	v_mfma_f32_16x16x32_bf16 v[20:23], v[162:165], v[206:209], v[20:23]
	v_mfma_f32_16x16x32_bf16 v[12:15], v[154:157], v[214:217], v[12:15]
	v_mfma_f32_16x16x32_bf16 v[4:7], v[162:165], v[214:217], v[4:7]
	s_setprio 0
	s_setprio 1
	v_mfma_f32_16x16x32_bf16 v[56:59], v[166:169], v[182:185], v[56:59]
	v_mfma_f32_16x16x32_bf16 v[48:51], v[174:177], v[182:185], v[48:51]
	v_mfma_f32_16x16x32_bf16 v[40:43], v[166:169], v[194:197], v[40:43]
	v_mfma_f32_16x16x32_bf16 v[32:35], v[174:177], v[194:197], v[32:35]
	v_mfma_f32_16x16x32_bf16 v[24:27], v[166:169], v[202:205], v[24:27]
	v_mfma_f32_16x16x32_bf16 v[16:19], v[174:177], v[202:205], v[16:19]
	v_mfma_f32_16x16x32_bf16 v[8:11], v[166:169], v[210:213], v[8:11]
	v_mfma_f32_16x16x32_bf16 v[0:3], v[174:177], v[210:213], v[0:3]
	v_mfma_f32_16x16x32_bf16 v[56:59], v[170:173], v[186:189], v[56:59]
	v_mfma_f32_16x16x32_bf16 v[48:51], v[178:181], v[186:189], v[48:51]
	v_mfma_f32_16x16x32_bf16 v[40:43], v[170:173], v[198:201], v[40:43]
	v_mfma_f32_16x16x32_bf16 v[32:35], v[178:181], v[198:201], v[32:35]
	v_mfma_f32_16x16x32_bf16 v[24:27], v[170:173], v[206:209], v[24:27]
	v_mfma_f32_16x16x32_bf16 v[16:19], v[178:181], v[206:209], v[16:19]
	v_mfma_f32_16x16x32_bf16 v[8:11], v[170:173], v[214:217], v[8:11]
	v_mfma_f32_16x16x32_bf16 v[0:3], v[178:181], v[214:217], v[0:3]
	s_setprio 0
	s_barrier
	s_add_i32 s63, s63, 2
	s_add_u32 s44, s44, 0x100
	s_addc_u32 s45, s45, 0
	s_add_u32 s61, s61, 0x100
	s_addc_u32 s62, s62, 0
	s_branch .LBB0_577
